# previous best plus: first grid barrier loads its 16 arrival counters back to back; first weight-transpose tile loads its rows back to back; padded to keep later code placement modulo 64 bytes
# speedup vs baseline: 1.0107x; 1.0107x over previous
.LBB0_23:
	s_lshr_b32 s2, s12, 7
	v_cvt_f32_ubyte0_e32 v3, s2
	v_rcp_iflag_f32_e32 v3, v3
	s_sub_i32 s20, 0, s2
	s_abs_i32 s19, s3
	s_ashr_i32 s18, s3, 31
	v_mul_f32_e32 v3, 0x4f7ffffe, v3
	v_cvt_u32_f32_e32 v3, v3
	v_mbcnt_lo_u32_b32 v2, -1, v2
	v_mbcnt_hi_u32_b32 v39, -1, v2
	v_lshlrev_b32_e32 v2, 2, v39
	v_readfirstlane_b32 s21, v3
	s_mul_i32 s20, s20, s21
	s_mul_hi_u32 s20, s21, s20
	s_add_i32 s21, s21, s20
	s_mul_hi_u32 s20, s19, s21
	s_mul_i32 s21, s20, s2
	s_sub_i32 s19, s19, s21
	s_add_i32 s21, s20, 1
	s_sub_i32 s23, s19, s2
	s_cmp_ge_u32 s19, s2
	s_cselect_b32 s20, s21, s20
	s_cselect_b32 s19, s23, s19
	s_add_i32 s21, s20, 1
	s_cmp_ge_u32 s19, s2
	s_cselect_b32 s19, s21, s20
	s_xor_b32 s19, s19, s18
	s_sub_i32 s19, s19, s18
	s_mul_i32 s2, s19, s2
	s_sub_i32 s2, s3, s2
	v_add_u32_e32 v38, s85, v39
	s_lshl_b32 s18, s2, 7
	v_and_b32_e32 v41, 0x7c, v2
	v_ashrrev_i32_e32 v42, 5, v38
	v_or_b32_e32 v3, s18, v41
	v_lshl_add_u32 v36, s19, 7, v42
	s_ashr_i32 s19, s18, 31
	v_mov_b32_e32 v2, 0
	v_cmp_gt_i32_e32 vcc, s22, v3
	v_lshlrev_b32_e32 v34, 2, v41
	v_mov_b32_e32 v6, 0
	v_mov_b32_e32 v7, 0
	v_mov_b32_e32 v8, 0
	v_mov_b32_e32 v9, 0
	v_mov_b32_e32 v2, 0
	v_mov_b32_e32 v3, 0
	v_mov_b32_e32 v4, 0
	v_mov_b32_e32 v5, 0
	v_mov_b32_e32 v6, 0
	v_mov_b32_e32 v7, 0
	v_mov_b32_e32 v8, 0
	v_mov_b32_e32 v9, 0
	v_mov_b32_e32 v10, 0
	v_mov_b32_e32 v11, 0
	v_mov_b32_e32 v12, 0
	v_mov_b32_e32 v13, 0
	v_mov_b32_e32 v14, 0
	v_mov_b32_e32 v15, 0
	v_mov_b32_e32 v16, 0
	v_mov_b32_e32 v17, 0
	v_mov_b32_e32 v18, 0
	v_mov_b32_e32 v19, 0
	v_mov_b32_e32 v20, 0
	v_mov_b32_e32 v21, 0
	v_mov_b32_e32 v22, 0
	v_mov_b32_e32 v23, 0
	v_mov_b32_e32 v24, 0
	v_mov_b32_e32 v25, 0
	v_mov_b32_e32 v26, 0
	v_mov_b32_e32 v27, 0
	v_mov_b32_e32 v28, 0
	v_mov_b32_e32 v29, 0
	v_mov_b32_e32 v30, 0
	v_mov_b32_e32 v31, 0
	v_mov_b32_e32 v32, 0
	v_mov_b32_e32 v33, 0
	v_mov_b32_e32 v35, 0
	s_and_saveexec_b64 s[20:21], vcc
	s_cbranch_execz .LBB0_47
	v_mad_i64_i32 v[202:203], s[24:25], v36, s22, 0
	v_lshl_add_u64 v[202:203], v[202:203], 2, s[14:15]
	v_lshl_add_u64 v[202:203], s[18:19], 2, v[202:203]
	v_lshl_add_u64 v[202:203], v[202:203], 0, v[34:35]
	global_load_dwordx4 v[6:9], v[202:203], off
	v_add_u32_e32 v200, 16, v36
	v_mad_i64_i32 v[202:203], s[24:25], v200, s22, 0
	v_lshl_add_u64 v[202:203], v[202:203], 2, s[14:15]
	v_lshl_add_u64 v[202:203], s[18:19], 2, v[202:203]
	v_lshl_add_u64 v[202:203], v[202:203], 0, v[34:35]
	global_load_dwordx4 v[2:5], v[202:203], off
	v_add_u32_e32 v200, 32, v36
	v_mad_i64_i32 v[202:203], s[24:25], v200, s22, 0
	v_lshl_add_u64 v[202:203], v[202:203], 2, s[14:15]
	v_lshl_add_u64 v[202:203], s[18:19], 2, v[202:203]
	v_lshl_add_u64 v[202:203], v[202:203], 0, v[34:35]
	global_load_dwordx4 v[14:17], v[202:203], off
	v_add_u32_e32 v200, 48, v36
	v_mad_i64_i32 v[202:203], s[24:25], v200, s22, 0
	v_lshl_add_u64 v[202:203], v[202:203], 2, s[14:15]
	v_lshl_add_u64 v[202:203], s[18:19], 2, v[202:203]
	v_lshl_add_u64 v[202:203], v[202:203], 0, v[34:35]
	global_load_dwordx4 v[10:13], v[202:203], off
	v_add_u32_e32 v200, 64, v36
	v_mad_i64_i32 v[202:203], s[24:25], v200, s22, 0
	v_lshl_add_u64 v[202:203], v[202:203], 2, s[14:15]
	v_lshl_add_u64 v[202:203], s[18:19], 2, v[202:203]
	v_lshl_add_u64 v[202:203], v[202:203], 0, v[34:35]
	global_load_dwordx4 v[22:25], v[202:203], off
	v_add_u32_e32 v200, 80, v36
	v_mad_i64_i32 v[202:203], s[24:25], v200, s22, 0
	v_lshl_add_u64 v[202:203], v[202:203], 2, s[14:15]
	v_lshl_add_u64 v[202:203], s[18:19], 2, v[202:203]
	v_lshl_add_u64 v[202:203], v[202:203], 0, v[34:35]
	global_load_dwordx4 v[18:21], v[202:203], off
	v_add_u32_e32 v200, 96, v36
	v_mad_i64_i32 v[202:203], s[24:25], v200, s22, 0
	v_lshl_add_u64 v[202:203], v[202:203], 2, s[14:15]
	v_lshl_add_u64 v[202:203], s[18:19], 2, v[202:203]
	v_lshl_add_u64 v[202:203], v[202:203], 0, v[34:35]
	global_load_dwordx4 v[30:33], v[202:203], off
	v_add_u32_e32 v200, 112, v36
	v_mad_i64_i32 v[202:203], s[22:23], v200, s22, 0
	v_lshl_add_u64 v[202:203], v[202:203], 2, s[14:15]
	v_lshl_add_u64 v[202:203], s[18:19], 2, v[202:203]
	v_lshl_add_u64 v[202:203], v[202:203], 0, v[34:35]
	global_load_dwordx4 v[26:29], v[202:203], off
	s_cmp_eq_u64 s[16:17], 0
	s_cbranch_scc1 .LBB0_47
	v_ashrrev_i32_e32 v37, 31, v36
	v_lshl_add_u64 v[202:203], v[36:37], 2, s[16:17]
	global_load_dword v210, v[202:203], off
	global_load_dword v211, v[202:203], off offset:64
	global_load_dword v212, v[202:203], off offset:128
	global_load_dword v213, v[202:203], off offset:192
	global_load_dword v214, v[202:203], off offset:256
	global_load_dword v215, v[202:203], off offset:320
	global_load_dword v216, v[202:203], off offset:384
	global_load_dword v217, v[202:203], off offset:448
	s_waitcnt vmcnt(0)
	v_mul_f32_e32 v6, v6, v210
	v_mul_f32_e32 v7, v7, v210
	v_mul_f32_e32 v8, v8, v210
	v_mul_f32_e32 v9, v9, v210
	v_mul_f32_e32 v2, v2, v211
	v_mul_f32_e32 v3, v3, v211
	v_mul_f32_e32 v4, v4, v211
	v_mul_f32_e32 v5, v5, v211
	v_mul_f32_e32 v14, v14, v212
	v_mul_f32_e32 v15, v15, v212
	v_mul_f32_e32 v16, v16, v212
	v_mul_f32_e32 v17, v17, v212
	v_mul_f32_e32 v10, v10, v213
	v_mul_f32_e32 v11, v11, v213
	v_mul_f32_e32 v12, v12, v213
	v_mul_f32_e32 v13, v13, v213
	v_mul_f32_e32 v22, v22, v214
	v_mul_f32_e32 v23, v23, v214
	v_mul_f32_e32 v24, v24, v214
	v_mul_f32_e32 v25, v25, v214
	v_mul_f32_e32 v18, v18, v215
	v_mul_f32_e32 v19, v19, v215
	v_mul_f32_e32 v20, v20, v215
	v_mul_f32_e32 v21, v21, v215
	v_mul_f32_e32 v30, v30, v216
	v_mul_f32_e32 v31, v31, v216
	v_mul_f32_e32 v32, v32, v216
	v_mul_f32_e32 v33, v33, v216
	v_mul_f32_e32 v26, v26, v217
	v_mul_f32_e32 v27, v27, v217
	v_mul_f32_e32 v28, v28, v217
	v_mul_f32_e32 v29, v29, v217
	s_nop 0
